# rowwise-mid: 16 loads issued up front with counted vmcnt instead of serialized reloads of v[24:27]
# speedup vs baseline: 1.0065x; 1.0065x over previous
; __device__ __forceinline__ void rowwise_phase(const Args& a, LAS unsigned char* lds, bool from_partials, bool has_y, bool has_h, bool xin_bf, int xout_mode, ...
;     ...
;         for (int r = wave * 4; r < 256; r += 32) {
;             float v[4][2][8]; v4u yv[4][2];
; #pragma unroll
;             for (int h = 0; h < 4; ++h)
; #pragma unroll
;                 for (int j = 0; j < 2; ++j) { const size_t off = ((size_t)tile * 256 + r + h) * DM + 8 * lane + 512 * j;
;                     if (xin_bf) unpack8(__builtin_nontemporal_load((const v4u*)((const bf16*)xin + off)), v[h][j]);
;                     else { const f32x4 p0 = __builtin_nontemporal_load((const f32x4*)((const float*)xin + off)), p1 = __builtin_nontemporal_load((const f32x4*)((const float*)xin + off + 4));
;                         v[h][j][0] = p0.x; v[h][j][1] = p0.y; v[h][j][2] = p0.z; v[h][j][3] = p0.w; v[h][j][4] = p1.x; v[h][j][5] = p1.y; v[h][j][6] = p1.z; v[h][j][7] = p1.w; }
;                     yv[h][j] = has_y ? __builtin_nontemporal_load((const v4u*)(y + off)) : (v4u){0u, 0u, 0u, 0u}; }
;             if (has_y) {
;                 float rstd[4];
; #pragma unroll
;                 for (int h = 0; h < 4; ++h) { float ss = 0.f;
; #pragma unroll
;                     for (int j = 0; j < 2; ++j) { float yf[8]; unpack8(yv[h][j], yf);
; #pragma unroll
;                         for (int e = 0; e < 8; ++e) ss += yf[e] * yf[e]; }
;                     rstd[h] = __builtin_amdgcn_rsqf(wave_sum(ss) * (1.0f / DM) + EPS); }
.LBB0_517:
	v_lshl_add_u64 v[10:11], v[4:5], 0, v[8:9]
	v_add_co_u32_e32 v28, vcc, 0x32000000, v10
	s_brev_b32 s16, 48
	s_nop 0
	v_addc_co_u32_e32 v29, vcc, 0, v11, vcc
	v_add_co_u32_e32 v30, vcc, s16, v10
	s_mov_b32 s16, 0x2a000000
	s_nop 0
	v_addc_co_u32_e32 v31, vcc, 0, v11, vcc
	v_add_co_u32_e32 v104, vcc, s68, v10
	v_add_u32_e32 v23, 32, v23
	s_nop 0
	v_addc_co_u32_e32 v105, vcc, 0, v11, vcc
	v_lshl_add_u64 v[8:9], v[8:9], 0, s[34:35]
	v_add_co_u32_e32 v232, vcc, s15, v10
	s_nop 1
	v_addc_co_u32_e32 v233, vcc, 0, v11, vcc
	global_load_dwordx4 v[200:203], v[28:29], off nt
	global_load_dwordx4 v[88:91], v[104:105], off offset:-4096 nt
	global_load_dwordx4 v[208:211], v[28:29], off offset:1024 nt
	global_load_dwordx4 v[96:99], v[30:31], off offset:1024 nt
	global_load_dwordx4 v[212:215], v[28:29], off offset:2048 nt
	global_load_dwordx4 v[100:103], v[30:31], off offset:2048 nt
	global_load_dwordx4 v[216:219], v[28:29], off offset:3072 nt
	global_load_dwordx4 v[106:109], v[30:31], off offset:3072 nt
	global_load_dwordx4 v[220:223], v[232:233], off nt
	global_load_dwordx4 v[110:113], v[104:105], off nt
	global_load_dwordx4 v[224:227], v[232:233], off offset:1024 nt
	global_load_dwordx4 v[114:117], v[104:105], off offset:1024 nt
	global_load_dwordx4 v[228:231], v[232:233], off offset:2048 nt
	global_load_dwordx4 v[118:121], v[104:105], off offset:2048 nt
	global_load_dwordx4 v[92:95], v[232:233], off offset:3072 nt
	global_load_dwordx4 v[156:159], v[104:105], off offset:3072 nt
	s_waitcnt vmcnt(15)
	v_lshlrev_b32_e32 v80, 16, v200
	v_and_b32_e32 v81, 0xffff0000, v200
	v_lshlrev_b32_e32 v82, 16, v201
	v_and_b32_e32 v83, 0xffff0000, v201
	v_lshlrev_b32_e32 v84, 16, v202
	v_and_b32_e32 v85, 0xffff0000, v202
	v_lshlrev_b32_e32 v86, 16, v203
	v_and_b32_e32 v87, 0xffff0000, v203
	s_waitcnt vmcnt(14)
	v_and_b32_e32 v130, 0xffff0000, v88
	s_waitcnt vmcnt(13)
	v_lshlrev_b32_e32 v69, 16, v208
	v_and_b32_e32 v72, 0xffff0000, v208
	v_lshlrev_b32_e32 v73, 16, v209
	v_and_b32_e32 v75, 0xffff0000, v209
	v_lshlrev_b32_e32 v76, 16, v210
	v_and_b32_e32 v77, 0xffff0000, v210
	v_lshlrev_b32_e32 v78, 16, v211
	v_and_b32_e32 v79, 0xffff0000, v211
	v_lshlrev_b32_e32 v131, 16, v88
	v_lshlrev_b32_e32 v129, 16, v89
	v_and_b32_e32 v128, 0xffff0000, v89
	v_lshlrev_b32_e32 v127, 16, v90
	v_and_b32_e32 v126, 0xffff0000, v90
	v_lshlrev_b32_e32 v125, 16, v91
	v_and_b32_e32 v124, 0xffff0000, v91
	s_waitcnt vmcnt(12)
	v_lshlrev_b32_e32 v91, 16, v98
	s_waitcnt vmcnt(11)
	v_lshlrev_b32_e32 v60, 16, v212
	v_and_b32_e32 v64, 0xffff0000, v212
	v_lshlrev_b32_e32 v65, 16, v213
	v_and_b32_e32 v67, 0xffff0000, v213
	v_lshlrev_b32_e32 v68, 16, v214
	v_and_b32_e32 v70, 0xffff0000, v214
	v_lshlrev_b32_e32 v71, 16, v215
	v_and_b32_e32 v74, 0xffff0000, v215
	v_and_b32_e32 v90, 0xffff0000, v98
	v_lshlrev_b32_e32 v89, 16, v99
	v_and_b32_e32 v88, 0xffff0000, v99
	s_waitcnt vmcnt(10)
	v_and_b32_e32 v138, 0xffff0000, v100
	s_waitcnt vmcnt(9)
	v_lshlrev_b32_e32 v48, 16, v216
	v_and_b32_e32 v52, 0xffff0000, v216
	v_lshlrev_b32_e32 v53, 16, v217
	v_and_b32_e32 v56, 0xffff0000, v217
	v_lshlrev_b32_e32 v57, 16, v218
	v_and_b32_e32 v61, 0xffff0000, v218
	v_lshlrev_b32_e32 v62, 16, v219
	v_and_b32_e32 v66, 0xffff0000, v219
	v_lshlrev_b32_e32 v139, 16, v100
	v_lshlrev_b32_e32 v137, 16, v101
	v_and_b32_e32 v136, 0xffff0000, v101
	v_lshlrev_b32_e32 v135, 16, v102
	v_and_b32_e32 v134, 0xffff0000, v102
	v_lshlrev_b32_e32 v133, 16, v103
	v_and_b32_e32 v132, 0xffff0000, v103
	s_waitcnt vmcnt(8)
	v_and_b32_e32 v103, 0xffff0000, v106
	v_lshlrev_b32_e32 v102, 16, v107
	v_and_b32_e32 v101, 0xffff0000, v107
	v_lshlrev_b32_e32 v100, 16, v108
	v_and_b32_e32 v99, 0xffff0000, v108
	v_lshlrev_b32_e32 v98, 16, v109
	s_waitcnt vmcnt(7)
	v_lshlrev_b32_e32 v45, 16, v220
	v_and_b32_e32 v49, 0xffff0000, v220
	v_lshlrev_b32_e32 v50, 16, v221
	v_and_b32_e32 v54, 0xffff0000, v221
	v_lshlrev_b32_e32 v55, 16, v222
	v_and_b32_e32 v58, 0xffff0000, v222
	v_lshlrev_b32_e32 v59, 16, v223
	v_and_b32_e32 v63, 0xffff0000, v223
	s_waitcnt vmcnt(6)
	v_and_b32_e32 v146, 0xffff0000, v110
	s_waitcnt vmcnt(5)
	v_lshlrev_b32_e32 v37, 16, v224
	v_and_b32_e32 v40, 0xffff0000, v224
	v_lshlrev_b32_e32 v41, 16, v225
	v_and_b32_e32 v43, 0xffff0000, v225
	v_lshlrev_b32_e32 v44, 16, v226
	v_and_b32_e32 v46, 0xffff0000, v226
	v_lshlrev_b32_e32 v47, 16, v227
	v_and_b32_e32 v51, 0xffff0000, v227
	v_mul_f32_e32 v104, v130, v130
	v_fmac_f32_e32 v104, v131, v131
	v_fmac_f32_e32 v104, v129, v129
	v_fmac_f32_e32 v104, v128, v128
	v_fmac_f32_e32 v104, v127, v127
	v_fmac_f32_e32 v104, v126, v126
	v_fmac_f32_e32 v104, v125, v125
	v_fmac_f32_e32 v104, v124, v124
	v_mul_f32_e32 v105, v138, v138
	v_fmac_f32_e32 v105, v139, v139
	v_fmac_f32_e32 v105, v137, v137
	v_fmac_f32_e32 v105, v136, v136
	v_fmac_f32_e32 v105, v135, v135
	v_fmac_f32_e32 v105, v134, v134
	v_fmac_f32_e32 v105, v133, v133
	v_fmac_f32_e32 v105, v132, v132
	v_lshlrev_b32_e32 v147, 16, v110
	v_mul_f32_e32 v122, v146, v146
	v_lshlrev_b32_e32 v145, 16, v111
	v_fmac_f32_e32 v122, v147, v147
	v_and_b32_e32 v144, 0xffff0000, v111
	v_fmac_f32_e32 v122, v145, v145
	v_lshlrev_b32_e32 v143, 16, v112
	v_fmac_f32_e32 v122, v144, v144
	v_and_b32_e32 v142, 0xffff0000, v112
	v_fmac_f32_e32 v122, v143, v143
	v_lshlrev_b32_e32 v141, 16, v113
	v_fmac_f32_e32 v122, v142, v142
	v_and_b32_e32 v140, 0xffff0000, v113
	v_fmac_f32_e32 v122, v141, v141
	v_fmac_f32_e32 v122, v140, v140
	s_waitcnt vmcnt(4)
	v_lshlrev_b32_e32 v113, 16, v114
	s_waitcnt vmcnt(3)
	v_lshlrev_b32_e32 v36, 16, v230
	s_waitcnt vmcnt(1)
; __device__ __forceinline__ void rowwise_phase(const Args& a, LAS unsigned char* lds, bool from_partials, bool has_y, bool has_h, bool xin_bf, int xout_mode, ...
;     ...
;                 for (int h = 0; h < 4; ++h) { float ss = 0.f;
; #pragma unroll
;                     for (int j = 0; j < 2; ++j) { float yf[8]; unpack8(yv[h][j], yf);
; #pragma unroll
;                         for (int e = 0; e < 8; ++e) ss += yf[e] * yf[e]; }
;                     rstd[h] = __builtin_amdgcn_rsqf(wave_sum(ss) * (1.0f / DM) + EPS); }
	v_lshlrev_b32_e32 v31, 16, v95
	v_and_b32_e32 v34, 0xffff0000, v95
	v_lshlrev_b32_e32 v95, 16, v96
	v_lshlrev_b32_e32 v28, 16, v94
	v_and_b32_e32 v30, 0xffff0000, v94
	v_and_b32_e32 v94, 0xffff0000, v96
	v_fmac_f32_e32 v104, v95, v95
	v_and_b32_e32 v38, 0xffff0000, v230
	v_lshlrev_b32_e32 v39, 16, v231
	v_and_b32_e32 v42, 0xffff0000, v231
	v_lshlrev_b32_e32 v26, 16, v93
	v_and_b32_e32 v27, 0xffff0000, v93
	v_lshlrev_b32_e32 v93, 16, v97
	v_fmac_f32_e32 v104, v94, v94
	v_lshlrev_b32_e32 v29, 16, v228
	v_and_b32_e32 v32, 0xffff0000, v228
	v_lshlrev_b32_e32 v33, 16, v229
	v_and_b32_e32 v35, 0xffff0000, v229
	v_lshlrev_b32_e32 v24, 16, v92
	v_and_b32_e32 v25, 0xffff0000, v92
	v_and_b32_e32 v92, 0xffff0000, v97
	v_fmac_f32_e32 v104, v93, v93
	v_fmac_f32_e32 v104, v92, v92
	v_fmac_f32_e32 v104, v91, v91
	v_fmac_f32_e32 v104, v90, v90
	v_fmac_f32_e32 v104, v89, v89
	v_fmac_f32_e32 v104, v88, v88
	ds_bpermute_b32 v96, v17, v104
	v_and_b32_e32 v112, 0xffff0000, v114
	v_fmac_f32_e32 v122, v113, v113
	v_lshlrev_b32_e32 v111, 16, v115
	v_fmac_f32_e32 v122, v112, v112
	s_waitcnt lgkmcnt(0)
	v_add_f32_e32 v96, v104, v96
	ds_bpermute_b32 v97, v18, v96
	v_lshlrev_b32_e32 v104, 16, v106
	v_fmac_f32_e32 v105, v104, v104
	v_fmac_f32_e32 v105, v103, v103
	v_fmac_f32_e32 v105, v102, v102
	s_waitcnt lgkmcnt(0)
	v_add_f32_e32 v96, v96, v97
	ds_bpermute_b32 v97, v19, v96
	v_fmac_f32_e32 v105, v101, v101
	v_fmac_f32_e32 v105, v100, v100
	v_fmac_f32_e32 v105, v99, v99
	v_fmac_f32_e32 v105, v98, v98
	s_waitcnt lgkmcnt(0)
	v_add_f32_e32 v96, v96, v97
	ds_bpermute_b32 v97, v20, v96
	v_and_b32_e32 v110, 0xffff0000, v115
	v_fmac_f32_e32 v122, v111, v111
	v_fmac_f32_e32 v122, v110, v110
	v_and_b32_e32 v108, 0xffff0000, v116
	s_waitcnt lgkmcnt(0)
	v_add_f32_e32 v96, v96, v97
	ds_bpermute_b32 v97, v21, v96
	v_lshlrev_b32_e32 v107, 16, v117
	v_and_b32_e32 v154, 0xffff0000, v118
	v_lshlrev_b32_e32 v155, 16, v118
	v_mul_f32_e32 v123, v154, v154
	s_waitcnt lgkmcnt(0)
	v_add_f32_e32 v96, v96, v97
	ds_bpermute_b32 v97, v22, v96
	v_lshlrev_b32_e32 v153, 16, v119
	v_fmac_f32_e32 v123, v155, v155
	v_and_b32_e32 v152, 0xffff0000, v119
	v_fmac_f32_e32 v123, v153, v153
	s_waitcnt lgkmcnt(0)
	v_add_f32_e32 v96, v96, v97
	v_and_b32_e32 v97, 0xffff0000, v109
	v_fmac_f32_e32 v105, v97, v97
	ds_bpermute_b32 v106, v17, v105
	v_lshlrev_b32_e32 v109, 16, v116
	v_fmac_f32_e32 v122, v109, v109
	v_fmac_f32_e32 v122, v108, v108
	v_fmac_f32_e32 v122, v107, v107
	s_waitcnt lgkmcnt(0)
	v_add_f32_e32 v105, v105, v106
	ds_bpermute_b32 v106, v18, v105
	v_lshlrev_b32_e32 v151, 16, v120
	v_fmac_f32_e32 v123, v152, v152
	v_and_b32_e32 v150, 0xffff0000, v120
	v_fmac_f32_e32 v123, v151, v151
	s_waitcnt lgkmcnt(0)
	v_add_f32_e32 v105, v105, v106
	ds_bpermute_b32 v106, v19, v105
	v_lshlrev_b32_e32 v149, 16, v121
	v_fmac_f32_e32 v123, v150, v150
	v_and_b32_e32 v148, 0xffff0000, v121
	v_fmac_f32_e32 v123, v149, v149
	s_waitcnt lgkmcnt(0)
	v_add_f32_e32 v105, v105, v106
	ds_bpermute_b32 v106, v20, v105
	v_fmac_f32_e32 v123, v148, v148
	s_waitcnt vmcnt(0)
	v_and_b32_e32 v121, 0xffff0000, v156
	v_lshlrev_b32_e32 v120, 16, v157
	v_and_b32_e32 v119, 0xffff0000, v157
	s_waitcnt lgkmcnt(0)
	v_add_f32_e32 v105, v105, v106
	ds_bpermute_b32 v106, v21, v105
	v_lshlrev_b32_e32 v118, 16, v158
	v_lshlrev_b32_e32 v116, 16, v159
	v_fmamk_f32 v96, v96, 0x3a800000, v194
	v_rsq_f32_e32 v96, v96
	s_waitcnt lgkmcnt(0)
	v_add_f32_e32 v105, v105, v106
	ds_bpermute_b32 v106, v22, v105
	v_mul_f32_e32 v124, v96, v124
	v_mul_f32_e32 v131, v96, v131
	v_mul_f32_e32 v130, v96, v130
	s_waitcnt lgkmcnt(0)
	v_add_f32_e32 v105, v105, v106
	v_and_b32_e32 v106, 0xffff0000, v117
	v_fmac_f32_e32 v122, v106, v106
	ds_bpermute_b32 v114, v17, v122
	v_and_b32_e32 v117, 0xffff0000, v158
	v_fmamk_f32 v105, v105, 0x3a800000, v194
	v_rsq_f32_e32 v105, v105
	v_mul_f32_e32 v129, v96, v129
	s_waitcnt lgkmcnt(0)
	v_add_f32_e32 v114, v122, v114
	ds_bpermute_b32 v115, v18, v114
	v_lshlrev_b32_e32 v122, 16, v156
	v_fmac_f32_e32 v123, v122, v122
	v_fmac_f32_e32 v123, v121, v121
	v_fmac_f32_e32 v123, v120, v120
	s_waitcnt lgkmcnt(0)
	v_add_f32_e32 v114, v114, v115
	ds_bpermute_b32 v115, v19, v114
	v_fmac_f32_e32 v123, v119, v119
	v_fmac_f32_e32 v123, v118, v118
	v_fmac_f32_e32 v123, v117, v117
	v_fmac_f32_e32 v123, v116, v116
	s_waitcnt lgkmcnt(0)
	v_add_f32_e32 v114, v114, v115
	ds_bpermute_b32 v115, v20, v114
	v_mul_f32_e32 v128, v96, v128
	v_mul_f32_e32 v127, v96, v127
	v_mul_f32_e32 v126, v96, v126
	v_mul_f32_e32 v125, v96, v125
	s_waitcnt lgkmcnt(0)
	v_add_f32_e32 v114, v114, v115
	ds_bpermute_b32 v115, v21, v114
	v_mul_f32_e32 v88, v96, v88
	v_mul_f32_e32 v95, v96, v95
	v_mul_f32_e32 v91, v96, v91
	v_mul_f32_e32 v90, v96, v90
	s_waitcnt lgkmcnt(0)
	v_add_f32_e32 v114, v114, v115
	ds_bpermute_b32 v115, v22, v114
	v_mul_f32_e32 v89, v96, v89
	v_mul_f32_e32 v94, v96, v94
	v_mul_f32_e32 v93, v96, v93
	v_mul_f32_e32 v92, v96, v92
	s_waitcnt lgkmcnt(0)
	v_add_f32_e32 v114, v114, v115
	v_and_b32_e32 v115, 0xffff0000, v159
	v_fmac_f32_e32 v123, v115, v115
	ds_bpermute_b32 v156, v17, v123
	v_fmamk_f32 v114, v114, 0x3a800000, v194
	v_rsq_f32_e32 v114, v114
	s_waitcnt lgkmcnt(0)
	v_add_f32_e32 v123, v123, v156
	ds_bpermute_b32 v156, v18, v123
	s_waitcnt lgkmcnt(0)
	v_add_f32_e32 v123, v123, v156
	ds_bpermute_b32 v156, v19, v123
	s_waitcnt lgkmcnt(0)
	v_add_f32_e32 v123, v123, v156
	ds_bpermute_b32 v156, v20, v123
	s_waitcnt lgkmcnt(0)
	v_add_f32_e32 v123, v123, v156
	ds_bpermute_b32 v156, v21, v123
	s_waitcnt lgkmcnt(0)
	v_add_f32_e32 v123, v123, v156
	ds_bpermute_b32 v156, v22, v123
	s_waitcnt lgkmcnt(0)
; #define LAS __attribute__((address_space(3)))
; #define LAS __attribute__((address_space(3)))
; __device__ __forceinline__ v4u pack8(const float (&f)[8]) { return (v4u){pk2(f[0], f[1]), pk2(f[2], f[3]), pk2(f[4], f[5]), pk2(f[6], f[7])}; }
; __device__ __forceinline__ void rowwise_phase(const Args& a, LAS unsigned char* lds, bool from_partials, bool has_y, bool has_h, bool xin_bf, int xout_mode, ...
;     ...
;                 for (int j = 0; j < 2; ++j) { const LAS float* gpp = vec + 8 * lane + 512 * j; const f32x4 g0 = *(const LAS f32x4*)gpp, g1 = *(const LAS f32x4*)(gpp + 4);
;                     const float gp[8] = {g0.x, g0.y, g0.z, g0.w, g1.x, g1.y, g1.z, g1.w};
; #pragma unroll
;                     for (int h = 0; h < 4; ++h) { float yf[8]; unpack8(yv[h][j], yf);
; #pragma unroll
;                         for (int e = 0; e < 8; ++e) v[h][j][e] += gp[e] * (yf[e] * rstd[h]); } }
;             }
;             if (xout_mode == 1) {
; #pragma unroll
;                 for (int h = 0; h < 4; ++h)
; #pragma unroll
;                     for (int j = 0; j < 2; ++j) { float* o = xout + ((size_t)tile * 256 + r + h) * DM + 8 * lane + 512 * j;
;                         __builtin_nontemporal_store((f32x4){v[h][j][0], v[h][j][1], v[h][j][2], v[h][j][3]}, (f32x4*)o); __builtin_nontemporal_store((f32x4){v[h][j][4], v[h][j][5], v[h][j][6], v[h][j][7]}, (f32x4*)(o + 4)); }
;             } else if (xout_mode == 2) {
; #pragma unroll
;                 for (int h = 0; h < 4; ++h)
; #pragma unroll
;                     for (int j = 0; j < 2; ++j) { const v4u w = pack8(v[h][j]);
;                         __builtin_nontemporal_store(w, (v4u*)(xoutb + ((size_t)tile * 256 + r + h) * DM + 8 * lane + 512 * j));
;                         unpack8(w, v[h][j]); }
;             }
;             if (has_h) {
;                 float rstd[4];
; #pragma unroll
;                 for (int h = 0; h < 4; ++h) { float ss = 0.f;
; #pragma unroll
;                     for (int j = 0; j < 2; ++j)
; #pragma unroll
;                         for (int e = 0; e < 8; ++e) ss += v[h][j][e] * v[h][j][e];
	v_add_f32_e32 v123, v123, v156
	ds_read_b128 v[156:159], v0
	ds_read_b128 v[174:177], v0 offset:16
	v_fmamk_f32 v123, v123, 0x3a800000, v194
	v_rsq_f32_e32 v123, v123
	s_waitcnt lgkmcnt(1)
	v_fmac_f32_e32 v80, v131, v156
	s_waitcnt lgkmcnt(0)
	v_fmac_f32_e32 v87, v124, v177
	v_mul_f32_e32 v124, v105, v139
	v_fmac_f32_e32 v60, v124, v156
	v_mul_f32_e32 v124, v105, v138
	v_fmac_f32_e32 v64, v124, v157
	v_mul_f32_e32 v124, v105, v137
	v_fmac_f32_e32 v65, v124, v158
	v_mul_f32_e32 v124, v105, v136
	v_fmac_f32_e32 v67, v124, v159
	v_mul_f32_e32 v124, v105, v135
	v_fmac_f32_e32 v68, v124, v174
	v_mul_f32_e32 v124, v105, v134
	v_fmac_f32_e32 v70, v124, v175
	v_mul_f32_e32 v124, v105, v133
	v_fmac_f32_e32 v71, v124, v176
	v_mul_f32_e32 v124, v105, v132
	v_fmac_f32_e32 v74, v124, v177
	v_mul_f32_e32 v124, v114, v147
	v_fmac_f32_e32 v45, v124, v156
	v_mul_f32_e32 v124, v114, v146
	v_fmac_f32_e32 v49, v124, v157
	v_mul_f32_e32 v124, v114, v145
	v_fmac_f32_e32 v50, v124, v158
	v_mul_f32_e32 v124, v114, v144
	v_fmac_f32_e32 v54, v124, v159
	v_mul_f32_e32 v124, v114, v143
	v_fmac_f32_e32 v55, v124, v174
	v_mul_f32_e32 v124, v114, v142
	v_fmac_f32_e32 v58, v124, v175
	v_mul_f32_e32 v124, v114, v141
	v_fmac_f32_e32 v59, v124, v176
	v_mul_f32_e32 v124, v114, v140
	v_fmac_f32_e32 v63, v124, v177
	v_mul_f32_e32 v124, v123, v155
	v_fmac_f32_e32 v29, v156, v124
	v_mul_f32_e32 v124, v123, v154
	v_fmac_f32_e32 v32, v157, v124
	v_mul_f32_e32 v124, v123, v153
	v_fmac_f32_e32 v33, v158, v124
	v_mul_f32_e32 v124, v123, v152
	v_fmac_f32_e32 v35, v159, v124
	v_mul_f32_e32 v124, v123, v151
	v_fmac_f32_e32 v36, v174, v124
	v_mul_f32_e32 v124, v123, v150
	v_fmac_f32_e32 v38, v175, v124
	v_mul_f32_e32 v124, v123, v149
	v_fmac_f32_e32 v39, v176, v124
	v_mul_f32_e32 v124, v123, v148
	v_fmac_f32_e32 v81, v130, v157
	v_fmac_f32_e32 v82, v129, v158
	v_fmac_f32_e32 v83, v128, v159
	v_fmac_f32_e32 v84, v127, v174
	v_fmac_f32_e32 v85, v126, v175
	v_fmac_f32_e32 v86, v125, v176
	v_fmac_f32_e32 v42, v177, v124
	ds_read_b128 v[124:127], v0 offset:2048
	ds_read_b128 v[128:131], v0 offset:2064
	v_cvt_pk_bf16_f32 v80, v80, v81
	v_cvt_pk_bf16_f32 v81, v82, v83
	v_cvt_pk_bf16_f32 v82, v84, v85
	v_add_co_u32_e32 v84, vcc, s16, v10
	s_waitcnt lgkmcnt(0)
	v_fmac_f32_e32 v79, v88, v131
	v_mul_f32_e32 v88, v105, v104
	v_fmac_f32_e32 v48, v88, v124
	v_mul_f32_e32 v88, v105, v103
	v_fmac_f32_e32 v52, v88, v125
	v_mul_f32_e32 v88, v105, v102
	v_fmac_f32_e32 v53, v88, v126
	v_mul_f32_e32 v88, v105, v101
	v_fmac_f32_e32 v56, v88, v127
	v_mul_f32_e32 v88, v105, v100
	v_fmac_f32_e32 v57, v88, v128
	v_mul_f32_e32 v88, v105, v99
	v_fmac_f32_e32 v61, v88, v129
	v_mul_f32_e32 v88, v105, v98
	v_fmac_f32_e32 v62, v88, v130
	v_mul_f32_e32 v88, v105, v97
	v_fmac_f32_e32 v66, v88, v131
	v_mul_f32_e32 v88, v114, v113
	v_fmac_f32_e32 v37, v88, v124
	v_mul_f32_e32 v88, v114, v112
	v_fmac_f32_e32 v40, v88, v125
	v_mul_f32_e32 v88, v114, v111
	v_fmac_f32_e32 v41, v88, v126
	v_mul_f32_e32 v88, v114, v110
	v_fmac_f32_e32 v43, v88, v127
	v_mul_f32_e32 v88, v114, v109
	v_fmac_f32_e32 v44, v88, v128
	v_mul_f32_e32 v88, v114, v108
	v_fmac_f32_e32 v46, v88, v129
	v_mul_f32_e32 v88, v114, v107
	v_fmac_f32_e32 v47, v88, v130
	v_mul_f32_e32 v88, v114, v106
	v_fmac_f32_e32 v51, v88, v131
	v_mul_f32_e32 v88, v123, v122
	v_fmac_f32_e32 v24, v124, v88
	v_mul_f32_e32 v88, v123, v121
	v_fmac_f32_e32 v25, v125, v88
	v_mul_f32_e32 v88, v123, v120
	v_fmac_f32_e32 v26, v126, v88
	v_mul_f32_e32 v88, v123, v119
	v_fmac_f32_e32 v27, v127, v88
	v_mul_f32_e32 v88, v123, v118
	v_fmac_f32_e32 v28, v128, v88
	v_mul_f32_e32 v88, v123, v117
	v_addc_co_u32_e32 v85, vcc, 0, v11, vcc
	v_fmac_f32_e32 v30, v129, v88
	v_mul_f32_e32 v88, v123, v116
	v_cvt_pk_bf16_f32 v83, v86, v87
	v_add_co_u32_e32 v86, vcc, s69, v10
	v_fmac_f32_e32 v69, v95, v124
	v_fmac_f32_e32 v76, v91, v128
	v_fmac_f32_e32 v77, v90, v129
	v_fmac_f32_e32 v78, v89, v130
	v_fmac_f32_e32 v31, v130, v88
	v_mul_f32_e32 v88, v123, v115
	v_addc_co_u32_e32 v87, vcc, 0, v11, vcc
	v_fmac_f32_e32 v72, v94, v125
	v_fmac_f32_e32 v73, v93, v126
	v_fmac_f32_e32 v75, v92, v127
	v_fmac_f32_e32 v34, v131, v88
	global_store_dwordx4 v[86:87], v[80:83], off offset:-4096 nt
	v_lshlrev_b32_e32 v88, 16, v80
	v_and_b32_e32 v89, 0xffff0000, v80
	v_lshlrev_b32_e32 v90, 16, v81
	v_and_b32_e32 v91, 0xffff0000, v81
	v_lshlrev_b32_e32 v92, 16, v82
	v_and_b32_e32 v93, 0xffff0000, v82
	v_lshlrev_b32_e32 v94, 16, v83
	v_and_b32_e32 v95, 0xffff0000, v83
	v_cvt_pk_bf16_f32 v80, v69, v72
	v_cvt_pk_bf16_f32 v81, v73, v75
	v_cvt_pk_bf16_f32 v82, v76, v77
	v_cvt_pk_bf16_f32 v83, v78, v79
	global_store_dwordx4 v[84:85], v[80:83], off offset:1024 nt
	v_cvt_pk_bf16_f32 v76, v60, v64
	v_cvt_pk_bf16_f32 v77, v65, v67
	v_cvt_pk_bf16_f32 v78, v68, v70
	v_cvt_pk_bf16_f32 v79, v71, v74
	global_store_dwordx4 v[84:85], v[76:79], off offset:2048 nt
	v_cvt_pk_bf16_f32 v68, v48, v52
	v_cvt_pk_bf16_f32 v69, v53, v56
	v_cvt_pk_bf16_f32 v70, v57, v61
	v_cvt_pk_bf16_f32 v71, v62, v66
	global_store_dwordx4 v[84:85], v[68:71], off offset:3072 nt
	v_cvt_pk_bf16_f32 v52, v45, v49
	v_cvt_pk_bf16_f32 v53, v50, v54
	v_cvt_pk_bf16_f32 v54, v55, v58
	v_cvt_pk_bf16_f32 v55, v59, v63
	global_store_dwordx4 v[86:87], v[52:55], off nt
	v_cvt_pk_bf16_f32 v48, v37, v40
	v_cvt_pk_bf16_f32 v49, v41, v43
	v_cvt_pk_bf16_f32 v50, v44, v46
	v_cvt_pk_bf16_f32 v51, v47, v51
	global_store_dwordx4 v[86:87], v[48:51], off offset:1024 nt
	v_cvt_pk_bf16_f32 v44, v29, v32
	v_cvt_pk_bf16_f32 v45, v33, v35
	v_cvt_pk_bf16_f32 v46, v36, v38
	v_cvt_pk_bf16_f32 v47, v39, v42
	global_store_dwordx4 v[86:87], v[44:47], off offset:2048 nt
	v_cvt_pk_bf16_f32 v24, v24, v25
	v_cvt_pk_bf16_f32 v25, v26, v27
	v_cvt_pk_bf16_f32 v26, v28, v30
	v_cvt_pk_bf16_f32 v27, v31, v34
	global_store_dwordx4 v[86:87], v[24:27], off offset:3072 nt
	v_lshlrev_b32_e32 v86, 16, v24
	v_and_b32_e32 v87, 0xffff0000, v24
	v_mul_f32_e32 v24, v89, v89
	v_fmac_f32_e32 v24, v88, v88
	v_fmac_f32_e32 v24, v90, v90
	v_fmac_f32_e32 v24, v91, v91
	v_fmac_f32_e32 v24, v92, v92
	v_fmac_f32_e32 v24, v93, v93
	v_fmac_f32_e32 v24, v94, v94
	v_lshlrev_b32_e32 v72, 16, v80
	v_fmac_f32_e32 v24, v95, v95
	v_and_b32_e32 v73, 0xffff0000, v80
	v_fmac_f32_e32 v24, v72, v72
	v_lshlrev_b32_e32 v75, 16, v81
	v_fmac_f32_e32 v24, v73, v73
	v_and_b32_e32 v80, 0xffff0000, v81
	v_fmac_f32_e32 v24, v75, v75
	v_lshlrev_b32_e32 v81, 16, v82
	v_fmac_f32_e32 v24, v80, v80
	v_and_b32_e32 v82, 0xffff0000, v82
	v_fmac_f32_e32 v24, v81, v81
	v_lshlrev_b32_e32 v96, 16, v83
	v_fmac_f32_e32 v24, v82, v82
	v_and_b32_e32 v83, 0xffff0000, v83
	v_fmac_f32_e32 v24, v96, v96
	v_fmac_f32_e32 v24, v83, v83
	v_lshlrev_b32_e32 v104, 16, v25
	v_and_b32_e32 v105, 0xffff0000, v25
	ds_bpermute_b32 v25, v17, v24
	v_and_b32_e32 v64, 0xffff0000, v76
	v_lshlrev_b32_e32 v60, 16, v76
	v_lshlrev_b32_e32 v65, 16, v77
	v_and_b32_e32 v67, 0xffff0000, v77
	s_waitcnt lgkmcnt(0)
; #define LAS __attribute__((address_space(3)))
; #define LAS __attribute__((address_space(3)))
; __device__ __forceinline__ void rowwise_phase(const Args& a, LAS unsigned char* lds, bool from_partials, bool has_y, bool has_h, bool xin_bf, int xout_mode, ...
;     ...
;                 for (int h = 0; h < 4; ++h) { float ss = 0.f;
; #pragma unroll
;                     for (int j = 0; j < 2; ++j)
; #pragma unroll
;                         for (int e = 0; e < 8; ++e) ss += v[h][j][e] * v[h][j][e];
;                     rstd[h] = __builtin_amdgcn_rsqf(wave_sum(ss) * (1.0f / DM) + EPS); }
; #pragma unroll
;                 for (int j = 0; j < 2; ++j) { const LAS float* gsp = vec + DM + 8 * lane + 512 * j; const LAS float* shp = vec + 2 * DM + 8 * lane + 512 * j;
;                     const f32x4 a0 = *(const LAS f32x4*)gsp, a1 = *(const LAS f32x4*)(gsp + 4), b0 = *(const LAS f32x4*)shp, b1 = *(const LAS f32x4*)(shp + 4);
	v_add_f32_e32 v24, v24, v25
	ds_bpermute_b32 v25, v18, v24
	v_lshlrev_b32_e32 v74, 16, v78
	v_and_b32_e32 v76, 0xffff0000, v78
	v_lshlrev_b32_e32 v77, 16, v79
	v_and_b32_e32 v78, 0xffff0000, v79
	s_waitcnt lgkmcnt(0)
	v_add_f32_e32 v24, v24, v25
	ds_bpermute_b32 v25, v19, v24
	v_lshlrev_b32_e32 v56, 16, v68
	v_and_b32_e32 v57, 0xffff0000, v68
	v_lshlrev_b32_e32 v61, 16, v69
	v_and_b32_e32 v62, 0xffff0000, v69
	s_waitcnt lgkmcnt(0)
	v_add_f32_e32 v24, v24, v25
	ds_bpermute_b32 v25, v20, v24
	v_lshlrev_b32_e32 v66, 16, v70
	v_and_b32_e32 v68, 0xffff0000, v70
	v_lshlrev_b32_e32 v69, 16, v71
	v_and_b32_e32 v70, 0xffff0000, v71
	s_waitcnt lgkmcnt(0)
	v_add_f32_e32 v24, v24, v25
	ds_bpermute_b32 v25, v21, v24
	v_lshlrev_b32_e32 v58, 16, v52
	v_and_b32_e32 v52, 0xffff0000, v52
	v_lshlrev_b32_e32 v59, 16, v53
	v_and_b32_e32 v53, 0xffff0000, v53
	s_waitcnt lgkmcnt(0)
	v_add_f32_e32 v24, v24, v25
	ds_bpermute_b32 v25, v22, v24
	v_lshlrev_b32_e32 v63, 16, v54
	v_and_b32_e32 v54, 0xffff0000, v54
	v_lshlrev_b32_e32 v71, 16, v55
	v_and_b32_e32 v55, 0xffff0000, v55
	s_waitcnt lgkmcnt(0)
	v_add_f32_e32 v24, v24, v25
	v_fmamk_f32 v24, v24, 0x3a800000, v194
	v_rsq_f32_e32 v110, v24
	v_mul_f32_e32 v24, v64, v64
	v_fmac_f32_e32 v24, v60, v60
	v_fmac_f32_e32 v24, v65, v65
	v_fmac_f32_e32 v24, v67, v67
	v_fmac_f32_e32 v24, v74, v74
	v_fmac_f32_e32 v24, v76, v76
	v_fmac_f32_e32 v24, v77, v77
	v_fmac_f32_e32 v24, v78, v78
	v_fmac_f32_e32 v24, v56, v56
	v_fmac_f32_e32 v24, v57, v57
	v_fmac_f32_e32 v24, v61, v61
	v_fmac_f32_e32 v24, v62, v62
	v_fmac_f32_e32 v24, v66, v66
	v_fmac_f32_e32 v24, v68, v68
	v_fmac_f32_e32 v24, v69, v69
	v_fmac_f32_e32 v24, v70, v70
	ds_bpermute_b32 v25, v17, v24
	v_lshlrev_b32_e32 v79, 16, v48
	v_and_b32_e32 v48, 0xffff0000, v48
	v_lshlrev_b32_e32 v84, 16, v49
	v_and_b32_e32 v49, 0xffff0000, v49
	s_waitcnt lgkmcnt(0)
	v_add_f32_e32 v24, v24, v25
	ds_bpermute_b32 v25, v18, v24
	v_lshlrev_b32_e32 v85, 16, v50
	v_and_b32_e32 v50, 0xffff0000, v50
	v_lshlrev_b32_e32 v97, 16, v51
	v_and_b32_e32 v51, 0xffff0000, v51
	s_waitcnt lgkmcnt(0)
	v_add_f32_e32 v24, v24, v25
	ds_bpermute_b32 v25, v19, v24
	v_and_b32_e32 v99, 0xffff0000, v44
	v_lshlrev_b32_e32 v98, 16, v44
	v_lshlrev_b32_e32 v100, 16, v45
	v_and_b32_e32 v101, 0xffff0000, v45
	s_waitcnt lgkmcnt(0)
	v_add_f32_e32 v24, v24, v25
	ds_bpermute_b32 v25, v20, v24
	v_lshlrev_b32_e32 v102, 16, v46
	v_and_b32_e32 v46, 0xffff0000, v46
	v_lshlrev_b32_e32 v103, 16, v47
	v_and_b32_e32 v47, 0xffff0000, v47
	s_waitcnt lgkmcnt(0)
	v_add_f32_e32 v24, v24, v25
	ds_bpermute_b32 v25, v21, v24
	v_lshlrev_b32_e32 v106, 16, v26
	v_and_b32_e32 v107, 0xffff0000, v26
	v_lshlrev_b32_e32 v108, 16, v27
	v_and_b32_e32 v109, 0xffff0000, v27
	s_waitcnt lgkmcnt(0)
	v_add_f32_e32 v24, v24, v25
	ds_bpermute_b32 v25, v22, v24
	v_mul_f32_e32 v40, v110, v88
	v_mul_f32_e32 v41, v110, v89
	v_mul_f32_e32 v42, v110, v90
	v_mul_f32_e32 v44, v110, v92
	s_waitcnt lgkmcnt(0)
	v_add_f32_e32 v24, v24, v25
	v_fmamk_f32 v24, v24, 0x3a800000, v194
	v_rsq_f32_e32 v111, v24
	v_mul_f32_e32 v24, v52, v52
	v_fmac_f32_e32 v24, v58, v58
	v_fmac_f32_e32 v24, v59, v59
	v_fmac_f32_e32 v24, v53, v53
	v_fmac_f32_e32 v24, v63, v63
	v_fmac_f32_e32 v24, v54, v54
	v_fmac_f32_e32 v24, v71, v71
	v_fmac_f32_e32 v24, v55, v55
	v_fmac_f32_e32 v24, v79, v79
	v_fmac_f32_e32 v24, v48, v48
	v_fmac_f32_e32 v24, v84, v84
	v_fmac_f32_e32 v24, v49, v49
	v_fmac_f32_e32 v24, v85, v85
	v_fmac_f32_e32 v24, v50, v50
	v_fmac_f32_e32 v24, v97, v97
	v_fmac_f32_e32 v24, v51, v51
	ds_bpermute_b32 v25, v17, v24
	v_mul_f32_e32 v43, v110, v91
	v_mul_f32_e32 v45, v110, v93
	v_mul_f32_e32 v88, v110, v94
	v_mul_f32_e32 v89, v110, v95
	s_waitcnt lgkmcnt(0)
	v_add_f32_e32 v24, v24, v25
	ds_bpermute_b32 v25, v18, v24
	s_waitcnt lgkmcnt(0)
	v_add_f32_e32 v24, v24, v25
	ds_bpermute_b32 v25, v19, v24
	s_waitcnt lgkmcnt(0)
	v_add_f32_e32 v24, v24, v25
	ds_bpermute_b32 v25, v20, v24
	s_waitcnt lgkmcnt(0)
	v_add_f32_e32 v24, v24, v25
	ds_bpermute_b32 v25, v21, v24
	s_waitcnt lgkmcnt(0)
	v_add_f32_e32 v24, v24, v25
	ds_bpermute_b32 v25, v22, v24
	s_waitcnt lgkmcnt(0)
	v_add_f32_e32 v24, v24, v25
	v_fmamk_f32 v24, v24, 0x3a800000, v194
	v_rsq_f32_e32 v112, v24
	v_mul_f32_e32 v24, v99, v99
	v_fmac_f32_e32 v24, v98, v98
	v_fmac_f32_e32 v24, v100, v100
	v_fmac_f32_e32 v24, v101, v101
	v_fmac_f32_e32 v24, v102, v102
	v_fmac_f32_e32 v24, v46, v46
	v_fmac_f32_e32 v24, v103, v103
	v_fmac_f32_e32 v24, v47, v47
	v_fmac_f32_e32 v24, v86, v86
	v_fmac_f32_e32 v24, v87, v87
	v_fmac_f32_e32 v24, v104, v104
	v_fmac_f32_e32 v24, v105, v105
	v_fmac_f32_e32 v24, v106, v106
	v_fmac_f32_e32 v24, v107, v107
	v_fmac_f32_e32 v24, v108, v108
	v_fmac_f32_e32 v24, v109, v109
	ds_bpermute_b32 v25, v17, v24
	v_mul_f32_e32 v55, v112, v55
	s_waitcnt lgkmcnt(0)
	v_add_f32_e32 v24, v24, v25
	ds_bpermute_b32 v25, v18, v24
	s_waitcnt lgkmcnt(0)
	v_add_f32_e32 v24, v24, v25
	ds_bpermute_b32 v25, v19, v24
	s_waitcnt lgkmcnt(0)
	v_add_f32_e32 v24, v24, v25
	ds_bpermute_b32 v25, v20, v24
	s_waitcnt lgkmcnt(0)
	v_add_f32_e32 v24, v24, v25
	ds_bpermute_b32 v25, v21, v24
	s_waitcnt lgkmcnt(0)
	v_add_f32_e32 v24, v24, v25
	ds_bpermute_b32 v25, v22, v24
	s_waitcnt lgkmcnt(0)
	v_add_f32_e32 v24, v24, v25
	v_fmamk_f32 v24, v24, 0x3a800000, v194
	v_rsq_f32_e32 v113, v24
	ds_read_b128 v[24:27], v0 offset:4096
	ds_read_b128 v[28:31], v0 offset:4112
	ds_read_b128 v[32:35], v0 offset:8192
	ds_read_b128 v[36:39], v0 offset:8208
	s_waitcnt lgkmcnt(1)
	v_fma_f32 v40, v40, v24, v32
	v_fma_f32 v41, v41, v25, v33
	v_fma_f32 v42, v42, v26, v34
	s_waitcnt lgkmcnt(0)
; #define LAS __attribute__((address_space(3)))
; #define LAS __attribute__((address_space(3)))
; __device__ __forceinline__ v4u pack8(const float (&f)[8]) { return (v4u){pk2(f[0], f[1]), pk2(f[2], f[3]), pk2(f[4], f[5]), pk2(f[6], f[7])}; }
; __device__ __forceinline__ void rowwise_phase(const Args& a, LAS unsigned char* lds, bool from_partials, bool has_y, bool has_h, bool xin_bf, int xout_mode, ...
;     ...
; #pragma unroll
;                 for (int j = 0; j < 2; ++j) { const LAS float* gsp = vec + DM + 8 * lane + 512 * j; const LAS float* shp = vec + 2 * DM + 8 * lane + 512 * j;
;                     const f32x4 a0 = *(const LAS f32x4*)gsp, a1 = *(const LAS f32x4*)(gsp + 4), b0 = *(const LAS f32x4*)shp, b1 = *(const LAS f32x4*)(shp + 4);
;                     const float gs[8] = {a0.x, a0.y, a0.z, a0.w, a1.x, a1.y, a1.z, a1.w}, sh[8] = {b0.x, b0.y, b0.z, b0.w, b1.x, b1.y, b1.z, b1.w};
; #pragma unroll
;                     for (int h = 0; h < 4; ++h) { float hv[8];
; #pragma unroll
;                         for (int e = 0; e < 8; ++e) hv[e] = v[h][j][e] * rstd[h] * gs[e] + sh[e];
;                         *(v4u*)(hout + ((size_t)tile * 256 + r + h) * DM + 8 * lane + 512 * j) = pack8(hv); } }
	v_fma_f32 v44, v44, v28, v36
	v_fma_f32 v43, v43, v27, v35
	v_fma_f32 v45, v45, v29, v37
	v_cvt_pk_bf16_f32 v40, v40, v41
	v_cvt_pk_bf16_f32 v41, v42, v43
	v_cvt_pk_bf16_f32 v42, v44, v45
	v_add_co_u32_e32 v44, vcc, s4, v10
	v_fma_f32 v88, v88, v30, v38
	s_nop 0
	v_addc_co_u32_e32 v45, vcc, 0, v11, vcc
	v_add_co_u32_e32 v10, vcc, s5, v10
	v_fma_f32 v89, v89, v31, v39
	s_nop 0
	v_addc_co_u32_e32 v11, vcc, 0, v11, vcc
	v_cvt_pk_bf16_f32 v43, v88, v89
	global_store_dwordx4 v[10:11], v[40:43], off offset:-4096
	v_fma_f32 v55, v55, v31, v39
	v_cmp_lt_i32_e32 vcc, s33, v23
	v_mul_f32_e32 v40, v111, v60
	v_fma_f32 v40, v40, v24, v32
	v_mul_f32_e32 v41, v111, v64
	v_mul_f32_e32 v42, v111, v65
	v_mul_f32_e32 v43, v111, v67
	v_fma_f32 v41, v41, v25, v33
	v_fma_f32 v42, v42, v26, v34
	v_fma_f32 v43, v43, v27, v35
	v_mul_f32_e32 v60, v111, v74
	v_mul_f32_e32 v64, v111, v76
	v_mul_f32_e32 v65, v111, v77
	v_mul_f32_e32 v67, v111, v78
	v_cvt_pk_bf16_f32 v40, v40, v41
	v_fma_f32 v60, v60, v28, v36
	v_fma_f32 v64, v64, v29, v37
	v_fma_f32 v65, v65, v30, v38
	v_fma_f32 v67, v67, v31, v39
	v_cvt_pk_bf16_f32 v41, v42, v43
	v_cvt_pk_bf16_f32 v42, v60, v64
	v_cvt_pk_bf16_f32 v43, v65, v67
	global_store_dwordx4 v[44:45], v[40:43], off offset:2048
	s_or_b64 s[54:55], vcc, s[54:55]
	s_nop 0
	v_mul_f32_e32 v40, v112, v58
	v_fma_f32 v40, v40, v24, v32
	v_mul_f32_e32 v41, v112, v52
	v_mul_f32_e32 v42, v112, v59
	v_mul_f32_e32 v43, v112, v53
	v_fma_f32 v41, v41, v25, v33
	v_fma_f32 v42, v42, v26, v34
	v_fma_f32 v43, v43, v27, v35
	v_mul_f32_e32 v52, v112, v63
	v_mul_f32_e32 v53, v112, v54
	v_mul_f32_e32 v54, v112, v71
	v_cvt_pk_bf16_f32 v40, v40, v41
	v_fma_f32 v52, v52, v28, v36
	v_fma_f32 v53, v53, v29, v37
	v_fma_f32 v54, v54, v30, v38
	v_cvt_pk_bf16_f32 v41, v42, v43
	v_cvt_pk_bf16_f32 v42, v52, v53
	v_cvt_pk_bf16_f32 v43, v54, v55
	global_store_dwordx4 v[10:11], v[40:43], off
	v_mul_f32_e32 v52, v110, v96
	v_mul_f32_e32 v53, v110, v83
	v_mul_f32_e32 v40, v113, v98
	v_fma_f32 v24, v24, v40, v32
	v_mul_f32_e32 v32, v113, v99
	v_fma_f32 v25, v25, v32, v33
	v_mul_f32_e32 v32, v113, v100
	v_fma_f32 v26, v26, v32, v34
	v_mul_f32_e32 v32, v113, v101
	v_fmac_f32_e32 v35, v27, v32
	v_mul_f32_e32 v27, v113, v102
	v_fma_f32 v27, v28, v27, v36
	v_mul_f32_e32 v28, v113, v46
	v_fma_f32 v28, v29, v28, v37
	v_mul_f32_e32 v29, v113, v103
	v_fma_f32 v29, v30, v29, v38
	v_mul_f32_e32 v30, v113, v47
	v_fmac_f32_e32 v39, v31, v30
	v_cvt_pk_bf16_f32 v24, v24, v25
	v_cvt_pk_bf16_f32 v25, v26, v35
	v_cvt_pk_bf16_f32 v26, v27, v28
	v_cvt_pk_bf16_f32 v27, v29, v39
	global_store_dwordx4 v[10:11], v[24:27], off offset:2048
	ds_read_b128 v[24:27], v0 offset:6144
	ds_read_b128 v[28:31], v0 offset:6160
	ds_read_b128 v[32:35], v0 offset:10240
	ds_read_b128 v[36:39], v0 offset:10256
	v_mul_f32_e32 v40, v110, v72
	v_mul_f32_e32 v41, v110, v73
	v_mul_f32_e32 v42, v110, v75
	s_waitcnt lgkmcnt(1)
	v_fma_f32 v40, v40, v24, v32
	v_mul_f32_e32 v43, v110, v80
	v_fma_f32 v41, v41, v25, v33
	v_fma_f32 v42, v42, v26, v34
	v_fma_f32 v43, v43, v27, v35
	v_mul_f32_e32 v46, v110, v81
	v_mul_f32_e32 v47, v110, v82
	v_cvt_pk_bf16_f32 v40, v40, v41
	s_waitcnt lgkmcnt(0)
	v_fma_f32 v46, v46, v28, v36
	v_fma_f32 v47, v47, v29, v37
	v_fma_f32 v52, v52, v30, v38
	v_fma_f32 v53, v53, v31, v39
	v_cvt_pk_bf16_f32 v41, v42, v43
	v_cvt_pk_bf16_f32 v42, v46, v47
	v_cvt_pk_bf16_f32 v43, v52, v53
	global_store_dwordx4 v[44:45], v[40:43], off offset:1024
	v_mul_f32_e32 v46, v111, v66
	v_mul_f32_e32 v47, v111, v68
	v_mul_f32_e32 v40, v111, v56
	v_fma_f32 v40, v40, v24, v32
	v_mul_f32_e32 v41, v111, v57
	v_mul_f32_e32 v42, v111, v61
	v_mul_f32_e32 v43, v111, v62
	v_fma_f32 v41, v41, v25, v33
	v_fma_f32 v42, v42, v26, v34
	v_fma_f32 v43, v43, v27, v35
	v_mul_f32_e32 v52, v111, v69
	v_mul_f32_e32 v53, v111, v70
	v_cvt_pk_bf16_f32 v40, v40, v41
	v_fma_f32 v46, v46, v28, v36
	v_fma_f32 v47, v47, v29, v37
	v_fma_f32 v52, v52, v30, v38
	v_fma_f32 v53, v53, v31, v39
	v_cvt_pk_bf16_f32 v41, v42, v43
	v_cvt_pk_bf16_f32 v42, v46, v47
	v_cvt_pk_bf16_f32 v43, v52, v53
	global_store_dwordx4 v[44:45], v[40:43], off offset:3072
	v_mul_f32_e32 v44, v112, v85
	v_mul_f32_e32 v45, v112, v50
	v_mul_f32_e32 v40, v112, v79
	v_fma_f32 v40, v40, v24, v32
	v_mul_f32_e32 v41, v112, v48
	v_mul_f32_e32 v42, v112, v84
	v_mul_f32_e32 v43, v112, v49
	v_fma_f32 v41, v41, v25, v33
	v_fma_f32 v42, v42, v26, v34
	v_fma_f32 v43, v43, v27, v35
	v_mul_f32_e32 v46, v112, v97
	v_mul_f32_e32 v47, v112, v51
	v_cvt_pk_bf16_f32 v40, v40, v41
	v_fma_f32 v44, v44, v28, v36
	v_fma_f32 v45, v45, v29, v37
	v_fma_f32 v46, v46, v30, v38
	v_fma_f32 v47, v47, v31, v39
	v_cvt_pk_bf16_f32 v41, v42, v43
	v_cvt_pk_bf16_f32 v42, v44, v45
	v_cvt_pk_bf16_f32 v43, v46, v47
	global_store_dwordx4 v[10:11], v[40:43], off offset:1024
	s_nop 1
	v_mul_f32_e32 v40, v113, v86
	v_fma_f32 v24, v40, v24, v32
	v_mul_f32_e32 v32, v113, v87
	v_fma_f32 v25, v32, v25, v33
	v_mul_f32_e32 v32, v113, v104
	v_fma_f32 v26, v32, v26, v34
	v_mul_f32_e32 v32, v113, v105
	v_fmac_f32_e32 v35, v32, v27
	v_mul_f32_e32 v27, v113, v106
	v_fma_f32 v27, v27, v28, v36
	v_mul_f32_e32 v28, v113, v107
	v_fma_f32 v28, v28, v29, v37
	v_mul_f32_e32 v29, v113, v108
	v_fma_f32 v29, v29, v30, v38
	v_mul_f32_e32 v30, v113, v109
	v_fmac_f32_e32 v39, v30, v31
	v_cvt_pk_bf16_f32 v24, v24, v25
	v_cvt_pk_bf16_f32 v25, v26, v35
	v_cvt_pk_bf16_f32 v26, v27, v28
	v_cvt_pk_bf16_f32 v27, v29, v39
	global_store_dwordx4 v[10:11], v[24:27], off offset:3072
	s_andn2_b64 exec, exec, s[54:55]
	s_cbranch_execnz .LBB0_517
	s_branch .LBB0_504
